# b11 + nt on KVQG epilogue stores
# speedup vs baseline: 1.0171x; 1.0046x over previous
.LBB0_645:
	s_lshl_b32 s8, s37, 12
	s_and_b32 s23, s8, 0x1000
	v_add_u32_e32 v138, s23, v176
	v_add_u32_e32 v138, 0xc00, v138
	s_cmp_gt_i32 s14, 5
	v_lshl_add_u32 v162, s36, 8, v174
	ds_read2_b32 v[168:169], v138 offset1:16
	ds_read2_b32 v[166:167], v138 offset0:32 offset1:48
	ds_read2_b32 v[164:165], v138 offset0:128 offset1:144
	ds_read2_b32 v[160:161], v138 offset0:160 offset1:176
	s_cselect_b64 s[42:43], -1, 0
	s_cmp_lt_u32 s14, 10
	s_cselect_b64 s[36:37], -1, 0
	s_cmp_gt_u32 s14, 9
	v_ashrrev_i32_e32 v163, 31, v162
	s_cselect_b64 s[40:41], -1, 0
	s_lshl_b32 s14, s14, 8
	v_lshlrev_b64 v[170:171], 11, v[162:163]
	s_waitcnt lgkmcnt(0)
	v_pk_mul_f32 v[134:135], v[134:135], v[168:169] op_sel_hi:[1,0]
	v_pk_mul_f32 v[132:133], v[132:133], v[168:169] op_sel_hi:[1,0]
	v_pk_mul_f32 v[130:131], v[130:131], v[168:169] op_sel_hi:[1,0]
	v_pk_mul_f32 v[128:129], v[128:129], v[168:169] op_sel_hi:[1,0]
	s_mov_b64 s[8:9], -1
	s_and_b64 vcc, exec, s[42:43]
	s_cbranch_vccz .LBB0_653
	s_and_b64 vcc, exec, s[40:41]
	s_cbranch_vccz .LBB0_650
	s_and_saveexec_b64 s[8:9], s[4:5]
	s_cbranch_execz .LBB0_649
	v_mul_f32_e32 v163, 0xbfb8aa3b, v134
	v_exp_f32_e32 v182, v163
	v_mul_f32_e32 v163, 0xbfb8aa3b, v135
	v_exp_f32_e32 v183, v163
	v_mul_f32_e32 v138, 0xbfb8aa3b, v132
	v_exp_f32_e32 v172, v138
	v_mul_f32_e32 v138, 0xbfb8aa3b, v128
	v_exp_f32_e32 v186, v138
	v_mul_f32_e32 v138, 0xbfb8aa3b, v133
	v_exp_f32_e32 v173, v138
	v_mul_f32_e32 v138, 0xbfb8aa3b, v129
	v_pk_add_f32 v[182:183], v[182:183], 1.0 op_sel_hi:[1,0]
	v_exp_f32_e32 v187, v138
	v_div_scale_f32 v138, s[38:39], v183, v183, 1.0
	v_rcp_f32_e32 v163, v138
	v_mul_f32_e32 v184, 0xbfb8aa3b, v130
	v_exp_f32_e32 v190, v184
	v_pk_add_f32 v[172:173], v[172:173], 1.0 op_sel_hi:[1,0]
	v_fma_f32 v184, -v138, v163, 1.0
	v_fmac_f32_e32 v163, v184, v163
	v_div_scale_f32 v184, vcc, 1.0, v183, 1.0
	v_mul_f32_e32 v185, v184, v163
	v_fma_f32 v189, -v138, v185, v184
	v_fmac_f32_e32 v185, v189, v163
	v_fma_f32 v138, -v138, v185, v184
	v_div_scale_f32 v184, s[38:39], v182, v182, 1.0
	v_rcp_f32_e32 v189, v184
	v_div_fmas_f32 v138, v138, v163, v185
	v_div_fixup_f32 v185, v138, v183, 1.0
	v_fma_f32 v138, -v184, v189, 1.0
	v_fmac_f32_e32 v189, v138, v189
	v_div_scale_f32 v138, vcc, 1.0, v182, 1.0
	v_mul_f32_e32 v163, v138, v189
	v_fma_f32 v183, -v184, v163, v138
	v_fmac_f32_e32 v163, v183, v189
	v_div_scale_f32 v183, s[38:39], v173, v173, 1.0
	v_rcp_f32_e32 v191, v183
	v_fma_f32 v138, -v184, v163, v138
	v_div_fmas_f32 v138, v138, v189, v163
	v_div_fixup_f32 v184, v138, v182, 1.0
	v_fma_f32 v138, -v183, v191, 1.0
	v_fmac_f32_e32 v191, v138, v191
	v_div_scale_f32 v138, vcc, 1.0, v173, 1.0
	v_mul_f32_e32 v163, v138, v191
	v_fma_f32 v182, -v183, v163, v138
	v_fmac_f32_e32 v163, v182, v191
	v_fma_f32 v138, -v183, v163, v138
	v_div_scale_f32 v182, s[38:39], v172, v172, 1.0
	v_div_fmas_f32 v138, v138, v191, v163
	v_rcp_f32_e32 v189, v182
	v_div_fixup_f32 v183, v138, v173, 1.0
	v_mul_f32_e32 v173, 0xbfb8aa3b, v131
	v_exp_f32_e32 v191, v173
	v_fma_f32 v138, -v182, v189, 1.0
	v_fmac_f32_e32 v189, v138, v189
	v_div_scale_f32 v138, vcc, 1.0, v172, 1.0
	v_pk_add_f32 v[190:191], v[190:191], 1.0 op_sel_hi:[1,0]
	v_mul_f32_e32 v163, v138, v189
	v_div_scale_f32 v192, s[38:39], v191, v191, 1.0
	v_fma_f32 v173, -v182, v163, v138
	v_rcp_f32_e32 v193, v192
	v_fmac_f32_e32 v163, v173, v189
	v_fma_f32 v138, -v182, v163, v138
	v_div_fmas_f32 v138, v138, v189, v163
	v_div_fixup_f32 v182, v138, v172, 1.0
	v_fma_f32 v138, -v192, v193, 1.0
	v_fmac_f32_e32 v193, v138, v193
	v_div_scale_f32 v138, vcc, 1.0, v191, 1.0
	v_mul_f32_e32 v163, v138, v193
	v_pk_add_f32 v[172:173], v[186:187], 1.0 op_sel_hi:[1,0]
	v_fma_f32 v186, -v192, v163, v138
	v_fmac_f32_e32 v163, v186, v193
	v_div_scale_f32 v186, s[38:39], v190, v190, 1.0
	v_rcp_f32_e32 v187, v186
	v_fma_f32 v138, -v192, v163, v138
	v_div_fmas_f32 v138, v138, v193, v163
	v_div_fixup_f32 v193, v138, v191, 1.0
	v_fma_f32 v138, -v186, v187, 1.0
	v_fmac_f32_e32 v187, v138, v187
	v_div_scale_f32 v138, vcc, 1.0, v190, 1.0
	v_mul_f32_e32 v163, v138, v187
	v_fma_f32 v189, -v186, v163, v138
	v_fmac_f32_e32 v163, v189, v187
	v_fma_f32 v138, -v186, v163, v138
	v_div_scale_f32 v186, s[38:39], v173, v173, 1.0
	v_rcp_f32_e32 v189, v186
	v_div_fmas_f32 v138, v138, v187, v163
	v_div_fixup_f32 v192, v138, v190, 1.0
	v_fma_f32 v138, -v186, v189, 1.0
	v_fmac_f32_e32 v189, v138, v189
	v_div_scale_f32 v138, vcc, 1.0, v173, 1.0
	v_mul_f32_e32 v163, v138, v189
	v_fma_f32 v187, -v186, v163, v138
	v_fmac_f32_e32 v163, v187, v189
	v_fma_f32 v138, -v186, v163, v138
	v_div_scale_f32 v186, s[38:39], v172, v172, 1.0
	v_rcp_f32_e32 v187, v186
	v_div_fmas_f32 v138, v138, v189, v163
	v_div_fixup_f32 v191, v138, v173, 1.0
	v_fma_f32 v138, -v186, v187, 1.0
	v_fmac_f32_e32 v187, v138, v187
	v_div_scale_f32 v138, vcc, 1.0, v172, 1.0
	v_mul_f32_e32 v163, v138, v187
	v_fma_f32 v173, -v186, v163, v138
	v_fmac_f32_e32 v163, v173, v187
	v_fma_f32 v138, -v186, v163, v138
	v_div_fmas_f32 v138, v138, v187, v163
	v_div_fixup_f32 v190, v138, v172, 1.0
	v_mad_i64_i32 v[172:173], s[38:39], v162, s53, v[150:151]
	global_store_dwordx4 v[172:173], v[182:185], off nt
	global_store_dwordx4 v[172:173], v[190:193], off offset:16 nt

.LBB0_650:
	s_andn2_b64 vcc, exec, s[8:9]
	s_cbranch_vccnz .LBB0_652
	v_pk_mul_f32 v[172:173], v[134:135], s[18:19] op_sel_hi:[1,0]
	v_pk_mul_f32 v[182:183], v[132:133], s[18:19] op_sel_hi:[1,0]
	v_lshlrev_b32_e32 v138, 1, v146
	v_cvt_pk_bf16_f32 v182, v182, v183
	v_cvt_pk_bf16_f32 v183, v172, v173
	v_lshl_add_u64 v[172:173], s[10:11], 0, v[170:171]
	v_lshl_add_u64 v[172:173], s[14:15], 1, v[172:173]
	v_pk_mul_f32 v[184:185], v[128:129], s[18:19] op_sel_hi:[1,0]
	v_lshl_add_u64 v[172:173], v[172:173], 0, v[138:139]
	v_pk_mul_f32 v[186:187], v[130:131], s[18:19] op_sel_hi:[1,0]
	v_cvt_pk_bf16_f32 v184, v184, v185
	s_nop 0
	v_cvt_pk_bf16_f32 v185, v186, v187
	global_store_dwordx4 v[172:173], v[182:185], off offset:-3072 nt

.LBB0_653:
	s_ashr_i32 s39, s14, 31
	s_mov_b32 s38, s14
	s_andn2_b64 vcc, exec, s[8:9]
	v_mad_i64_i32 v[172:173], s[8:9], v162, s61, 0
	s_cbranch_vccnz .LBB0_655
	v_cvt_pk_bf16_f32 v132, v132, v133
	v_cvt_pk_bf16_f32 v133, v134, v135
	v_cvt_pk_bf16_f32 v134, v128, v129
	v_lshl_add_u64 v[128:129], s[24:25], 0, v[172:173]
	v_lshl_add_u64 v[128:129], s[38:39], 1, v[128:129]
	v_lshlrev_b32_e32 v138, 1, v146
	v_lshl_add_u64 v[128:129], v[128:129], 0, v[138:139]
	v_cvt_pk_bf16_f32 v135, v130, v131
	global_store_dwordx4 v[128:129], v[132:135], off nt

.LBB0_662:
	v_lshlrev_b32_e32 v138, 1, v146
	v_lshl_add_u64 v[124:125], v[132:133], 0, v[138:139]
	global_store_dwordx4 v[124:125], v[120:123], off offset:256 nt
.LBB0_663:
	s_nop 1
	v_or_b32_e32 v122, 16, v162
	v_ashrrev_i32_e32 v123, 31, v122
	v_mov_b32_e32 v124, v169
	v_lshlrev_b64 v[120:121], 11, v[122:123]
	v_pk_mul_f32 v[118:119], v[118:119], v[124:125] op_sel_hi:[1,0]
	v_pk_mul_f32 v[116:117], v[116:117], v[124:125] op_sel_hi:[1,0]
	v_pk_mul_f32 v[114:115], v[114:115], v[124:125] op_sel_hi:[1,0]
	v_pk_mul_f32 v[112:113], v[112:113], v[124:125] op_sel_hi:[1,0]
	s_and_b64 vcc, exec, s[8:9]
	s_mov_b64 s[42:43], -1
	s_cbranch_vccnz .LBB0_671
	s_andn2_b64 vcc, exec, s[40:41]
	s_cbranch_vccnz .LBB0_668
	s_and_saveexec_b64 s[42:43], s[4:5]
	s_cbranch_execz .LBB0_667
	v_mul_f32_e32 v125, 0xbfb8aa3b, v118
	v_exp_f32_e32 v126, v125
	v_mul_f32_e32 v125, 0xbfb8aa3b, v119
	v_exp_f32_e32 v127, v125
	v_mul_f32_e32 v123, 0xbfb8aa3b, v116
	v_exp_f32_e32 v124, v123
	v_mul_f32_e32 v123, 0xbfb8aa3b, v112
	v_exp_f32_e32 v128, v123
	v_mul_f32_e32 v123, 0xbfb8aa3b, v117
	v_exp_f32_e32 v125, v123
	v_mul_f32_e32 v123, 0xbfb8aa3b, v113
	v_pk_add_f32 v[126:127], v[126:127], 1.0 op_sel_hi:[1,0]
	v_exp_f32_e32 v129, v123
	v_div_scale_f32 v123, s[44:45], v127, v127, 1.0
	v_rcp_f32_e32 v131, v123
	v_pk_add_f32 v[124:125], v[124:125], 1.0 op_sel_hi:[1,0]
	v_mul_f32_e32 v130, 0xbfb8aa3b, v114
	v_exp_f32_e32 v130, v130
	v_fma_f32 v132, -v123, v131, 1.0
	v_fmac_f32_e32 v131, v132, v131
	v_div_scale_f32 v132, vcc, 1.0, v127, 1.0
	v_mul_f32_e32 v133, v132, v131
	v_fma_f32 v134, -v123, v133, v132
	v_fmac_f32_e32 v133, v134, v131
	v_fma_f32 v123, -v123, v133, v132
	v_div_scale_f32 v132, s[44:45], v126, v126, 1.0
	v_rcp_f32_e32 v134, v132
	v_div_fmas_f32 v123, v123, v131, v133
	v_div_fixup_f32 v127, v123, v127, 1.0
	v_pk_add_f32 v[128:129], v[128:129], 1.0 op_sel_hi:[1,0]
	v_fma_f32 v123, -v132, v134, 1.0
	v_fmac_f32_e32 v134, v123, v134
	v_div_scale_f32 v123, vcc, 1.0, v126, 1.0
	v_mul_f32_e32 v131, v123, v134
	v_fma_f32 v133, -v132, v131, v123
	v_fmac_f32_e32 v131, v133, v134
	v_fma_f32 v123, -v132, v131, v123
	v_div_scale_f32 v132, s[44:45], v125, v125, 1.0
	v_rcp_f32_e32 v133, v132
	v_div_fmas_f32 v123, v123, v134, v131
	v_div_fixup_f32 v126, v123, v126, 1.0
	v_fma_f32 v123, -v132, v133, 1.0
	v_fmac_f32_e32 v133, v123, v133
	v_div_scale_f32 v123, vcc, 1.0, v125, 1.0
	v_mul_f32_e32 v131, v123, v133
	v_fma_f32 v134, -v132, v131, v123
	v_fmac_f32_e32 v131, v134, v133
	v_fma_f32 v123, -v132, v131, v123
	v_div_scale_f32 v132, s[44:45], v124, v124, 1.0
	v_rcp_f32_e32 v134, v132
	v_div_fmas_f32 v123, v123, v133, v131
	v_mul_f32_e32 v131, 0xbfb8aa3b, v115
	v_div_fixup_f32 v125, v123, v125, 1.0
	v_fma_f32 v123, -v132, v134, 1.0
	v_exp_f32_e32 v131, v131
	v_fmac_f32_e32 v134, v123, v134
	v_div_scale_f32 v123, vcc, 1.0, v124, 1.0
	v_mul_f32_e32 v133, v123, v134
	v_fma_f32 v135, -v132, v133, v123
	v_fmac_f32_e32 v133, v135, v134
	v_pk_add_f32 v[130:131], v[130:131], 1.0 op_sel_hi:[1,0]
	v_fma_f32 v123, -v132, v133, v123
	v_div_scale_f32 v132, s[44:45], v131, v131, 1.0
	v_rcp_f32_e32 v135, v132
	v_div_fmas_f32 v123, v123, v134, v133
	v_div_fixup_f32 v124, v123, v124, 1.0
	v_fma_f32 v123, -v132, v135, 1.0
	v_fmac_f32_e32 v135, v123, v135
	v_div_scale_f32 v123, vcc, 1.0, v131, 1.0
	v_mul_f32_e32 v133, v123, v135
	v_fma_f32 v134, -v132, v133, v123
	v_fmac_f32_e32 v133, v134, v135
	v_fma_f32 v123, -v132, v133, v123
	v_div_scale_f32 v132, s[44:45], v130, v130, 1.0
	v_rcp_f32_e32 v134, v132
	v_div_fmas_f32 v123, v123, v135, v133
	v_div_fixup_f32 v131, v123, v131, 1.0
	v_fma_f32 v123, -v132, v134, 1.0
	v_fmac_f32_e32 v134, v123, v134
	v_div_scale_f32 v123, vcc, 1.0, v130, 1.0
	v_mul_f32_e32 v133, v123, v134
	v_fma_f32 v135, -v132, v133, v123
	v_fmac_f32_e32 v133, v135, v134
	v_fma_f32 v123, -v132, v133, v123
	v_div_scale_f32 v132, s[44:45], v129, v129, 1.0
	v_rcp_f32_e32 v135, v132
	v_div_fmas_f32 v123, v123, v134, v133
	v_div_fixup_f32 v130, v123, v130, 1.0
	v_fma_f32 v123, -v132, v135, 1.0
	v_fmac_f32_e32 v135, v123, v135
	v_div_scale_f32 v123, vcc, 1.0, v129, 1.0
	v_mul_f32_e32 v133, v123, v135
	v_fma_f32 v134, -v132, v133, v123
	v_fmac_f32_e32 v133, v134, v135
	v_fma_f32 v123, -v132, v133, v123
	v_div_scale_f32 v132, s[44:45], v128, v128, 1.0
	v_rcp_f32_e32 v134, v132
	v_div_fmas_f32 v123, v123, v135, v133
	v_div_fixup_f32 v129, v123, v129, 1.0
	v_fma_f32 v123, -v132, v134, 1.0
	v_fmac_f32_e32 v134, v123, v134
	v_div_scale_f32 v123, vcc, 1.0, v128, 1.0
	v_mul_f32_e32 v133, v123, v134
	v_fma_f32 v135, -v132, v133, v123
	v_fmac_f32_e32 v133, v135, v134
	v_fma_f32 v123, -v132, v133, v123
	v_div_fmas_f32 v123, v123, v134, v133
	v_mad_i64_i32 v[132:133], s[44:45], v122, s53, v[150:151]
	v_div_fixup_f32 v128, v123, v128, 1.0
	global_store_dwordx4 v[132:133], v[124:127], off nt
	global_store_dwordx4 v[132:133], v[128:131], off offset:16 nt

.LBB0_668:
	s_andn2_b64 vcc, exec, s[42:43]
	s_cbranch_vccnz .LBB0_670
	v_pk_mul_f32 v[126:127], v[118:119], s[18:19] op_sel_hi:[1,0]
	v_pk_mul_f32 v[124:125], v[116:117], s[18:19] op_sel_hi:[1,0]
	v_pk_mul_f32 v[128:129], v[114:115], s[18:19] op_sel_hi:[1,0]
	v_pk_mul_f32 v[130:131], v[112:113], s[18:19] op_sel_hi:[1,0]
	v_cvt_pk_bf16_f32 v124, v124, v125
	v_cvt_pk_bf16_f32 v125, v126, v127
	v_lshlrev_b32_e32 v138, 1, v146
	v_cvt_pk_bf16_f32 v126, v130, v131
	v_cvt_pk_bf16_f32 v127, v128, v129
	v_lshl_add_u64 v[128:129], s[10:11], 0, v[120:121]
	v_lshl_add_u64 v[128:129], s[14:15], 1, v[128:129]
	v_lshl_add_u64 v[128:129], v[128:129], 0, v[138:139]
	global_store_dwordx4 v[128:129], v[124:127], off offset:-3072 nt

.LBB0_671:
	s_andn2_b64 vcc, exec, s[42:43]
	v_mad_i64_i32 v[122:123], s[42:43], v122, s61, 0
	s_cbranch_vccnz .LBB0_673
	v_cvt_pk_bf16_f32 v116, v116, v117
	v_cvt_pk_bf16_f32 v117, v118, v119
	v_cvt_pk_bf16_f32 v118, v112, v113
	v_lshl_add_u64 v[112:113], s[24:25], 0, v[122:123]
	v_lshl_add_u64 v[112:113], s[38:39], 1, v[112:113]
	v_lshlrev_b32_e32 v138, 1, v146
	v_lshl_add_u64 v[112:113], v[112:113], 0, v[138:139]
	v_cvt_pk_bf16_f32 v119, v114, v115
	global_store_dwordx4 v[112:113], v[116:119], off nt

.LBB0_679:
	s_andn2_b64 vcc, exec, s[44:45]
	s_cbranch_vccnz .LBB0_681
	v_lshlrev_b32_e32 v138, 1, v146
	v_lshl_add_u64 v[108:109], v[116:117], 0, v[138:139]
	global_store_dwordx4 v[108:109], v[104:107], off offset:256 nt
.LBB0_681:
	s_nop 1
	v_or_b32_e32 v106, 32, v162
	v_ashrrev_i32_e32 v107, 31, v106
	v_lshlrev_b64 v[104:105], 11, v[106:107]
	v_pk_mul_f32 v[102:103], v[102:103], v[166:167] op_sel_hi:[1,0]
	v_pk_mul_f32 v[100:101], v[100:101], v[166:167] op_sel_hi:[1,0]
	v_pk_mul_f32 v[98:99], v[98:99], v[166:167] op_sel_hi:[1,0]
	v_pk_mul_f32 v[96:97], v[96:97], v[166:167] op_sel_hi:[1,0]
	s_and_b64 vcc, exec, s[8:9]
	s_mov_b64 s[42:43], -1
	s_cbranch_vccnz .LBB0_689
	s_andn2_b64 vcc, exec, s[40:41]
	s_cbranch_vccnz .LBB0_686
	s_and_saveexec_b64 s[42:43], s[4:5]
	s_cbranch_execz .LBB0_685
	v_mul_f32_e32 v109, 0xbfb8aa3b, v102
	v_exp_f32_e32 v110, v109
	v_mul_f32_e32 v109, 0xbfb8aa3b, v103
	v_exp_f32_e32 v111, v109
	v_mul_f32_e32 v107, 0xbfb8aa3b, v100
	v_exp_f32_e32 v108, v107
	v_mul_f32_e32 v107, 0xbfb8aa3b, v96
	v_exp_f32_e32 v112, v107
	v_mul_f32_e32 v107, 0xbfb8aa3b, v101
	v_exp_f32_e32 v109, v107
	v_mul_f32_e32 v107, 0xbfb8aa3b, v97
	v_pk_add_f32 v[110:111], v[110:111], 1.0 op_sel_hi:[1,0]
	v_exp_f32_e32 v113, v107
	v_div_scale_f32 v107, s[44:45], v111, v111, 1.0
	v_rcp_f32_e32 v115, v107
	v_pk_add_f32 v[108:109], v[108:109], 1.0 op_sel_hi:[1,0]
	v_mul_f32_e32 v114, 0xbfb8aa3b, v98
	v_exp_f32_e32 v114, v114
	v_fma_f32 v116, -v107, v115, 1.0
	v_fmac_f32_e32 v115, v116, v115
	v_div_scale_f32 v116, vcc, 1.0, v111, 1.0
	v_mul_f32_e32 v117, v116, v115
	v_fma_f32 v118, -v107, v117, v116
	v_fmac_f32_e32 v117, v118, v115
	v_fma_f32 v107, -v107, v117, v116
	v_div_scale_f32 v116, s[44:45], v110, v110, 1.0
	v_rcp_f32_e32 v118, v116
	v_div_fmas_f32 v107, v107, v115, v117
	v_div_fixup_f32 v111, v107, v111, 1.0
	v_pk_add_f32 v[112:113], v[112:113], 1.0 op_sel_hi:[1,0]
	v_fma_f32 v107, -v116, v118, 1.0
	v_fmac_f32_e32 v118, v107, v118
	v_div_scale_f32 v107, vcc, 1.0, v110, 1.0
	v_mul_f32_e32 v115, v107, v118
	v_fma_f32 v117, -v116, v115, v107
	v_fmac_f32_e32 v115, v117, v118
	v_fma_f32 v107, -v116, v115, v107
	v_div_scale_f32 v116, s[44:45], v109, v109, 1.0
	v_rcp_f32_e32 v117, v116
	v_div_fmas_f32 v107, v107, v118, v115
	v_div_fixup_f32 v110, v107, v110, 1.0
	v_fma_f32 v107, -v116, v117, 1.0
	v_fmac_f32_e32 v117, v107, v117
	v_div_scale_f32 v107, vcc, 1.0, v109, 1.0
	v_mul_f32_e32 v115, v107, v117
	v_fma_f32 v118, -v116, v115, v107
	v_fmac_f32_e32 v115, v118, v117
	v_fma_f32 v107, -v116, v115, v107
	v_div_scale_f32 v116, s[44:45], v108, v108, 1.0
	v_rcp_f32_e32 v118, v116
	v_div_fmas_f32 v107, v107, v117, v115
	v_mul_f32_e32 v115, 0xbfb8aa3b, v99
	v_div_fixup_f32 v109, v107, v109, 1.0
	v_fma_f32 v107, -v116, v118, 1.0
	v_exp_f32_e32 v115, v115
	v_fmac_f32_e32 v118, v107, v118
	v_div_scale_f32 v107, vcc, 1.0, v108, 1.0
	v_mul_f32_e32 v117, v107, v118
	v_fma_f32 v119, -v116, v117, v107
	v_fmac_f32_e32 v117, v119, v118
	v_pk_add_f32 v[114:115], v[114:115], 1.0 op_sel_hi:[1,0]
	v_fma_f32 v107, -v116, v117, v107
	v_div_scale_f32 v116, s[44:45], v115, v115, 1.0
	v_rcp_f32_e32 v119, v116
	v_div_fmas_f32 v107, v107, v118, v117
	v_div_fixup_f32 v108, v107, v108, 1.0
	v_fma_f32 v107, -v116, v119, 1.0
	v_fmac_f32_e32 v119, v107, v119
	v_div_scale_f32 v107, vcc, 1.0, v115, 1.0
	v_mul_f32_e32 v117, v107, v119
	v_fma_f32 v118, -v116, v117, v107
	v_fmac_f32_e32 v117, v118, v119
	v_fma_f32 v107, -v116, v117, v107
	v_div_scale_f32 v116, s[44:45], v114, v114, 1.0
	v_rcp_f32_e32 v118, v116
	v_div_fmas_f32 v107, v107, v119, v117
	v_div_fixup_f32 v115, v107, v115, 1.0
	v_fma_f32 v107, -v116, v118, 1.0
	v_fmac_f32_e32 v118, v107, v118
	v_div_scale_f32 v107, vcc, 1.0, v114, 1.0
	v_mul_f32_e32 v117, v107, v118
	v_fma_f32 v119, -v116, v117, v107
	v_fmac_f32_e32 v117, v119, v118
	v_fma_f32 v107, -v116, v117, v107
	v_div_scale_f32 v116, s[44:45], v113, v113, 1.0
	v_rcp_f32_e32 v119, v116
	v_div_fmas_f32 v107, v107, v118, v117
	v_div_fixup_f32 v114, v107, v114, 1.0
	v_fma_f32 v107, -v116, v119, 1.0
	v_fmac_f32_e32 v119, v107, v119
	v_div_scale_f32 v107, vcc, 1.0, v113, 1.0
	v_mul_f32_e32 v117, v107, v119
	v_fma_f32 v118, -v116, v117, v107
	v_fmac_f32_e32 v117, v118, v119
	v_fma_f32 v107, -v116, v117, v107
	v_div_scale_f32 v116, s[44:45], v112, v112, 1.0
	v_rcp_f32_e32 v118, v116
	v_div_fmas_f32 v107, v107, v119, v117
	v_div_fixup_f32 v113, v107, v113, 1.0
	v_fma_f32 v107, -v116, v118, 1.0
	v_fmac_f32_e32 v118, v107, v118
	v_div_scale_f32 v107, vcc, 1.0, v112, 1.0
	v_mul_f32_e32 v117, v107, v118
	v_fma_f32 v119, -v116, v117, v107
	v_fmac_f32_e32 v117, v119, v118
	v_fma_f32 v107, -v116, v117, v107
	v_div_fmas_f32 v107, v107, v118, v117
	v_mad_i64_i32 v[116:117], s[44:45], v106, s53, v[150:151]
	v_div_fixup_f32 v112, v107, v112, 1.0
	global_store_dwordx4 v[116:117], v[108:111], off nt
	global_store_dwordx4 v[116:117], v[112:115], off offset:16 nt

.LBB0_686:
	s_andn2_b64 vcc, exec, s[42:43]
	s_cbranch_vccnz .LBB0_688
	v_pk_mul_f32 v[110:111], v[102:103], s[18:19] op_sel_hi:[1,0]
	v_pk_mul_f32 v[108:109], v[100:101], s[18:19] op_sel_hi:[1,0]
	v_pk_mul_f32 v[112:113], v[98:99], s[18:19] op_sel_hi:[1,0]
	v_pk_mul_f32 v[114:115], v[96:97], s[18:19] op_sel_hi:[1,0]
	v_cvt_pk_bf16_f32 v108, v108, v109
	v_cvt_pk_bf16_f32 v109, v110, v111
	v_lshlrev_b32_e32 v138, 1, v146
	v_cvt_pk_bf16_f32 v110, v114, v115
	v_cvt_pk_bf16_f32 v111, v112, v113
	v_lshl_add_u64 v[112:113], s[10:11], 0, v[104:105]
	v_lshl_add_u64 v[112:113], s[14:15], 1, v[112:113]
	v_lshl_add_u64 v[112:113], v[112:113], 0, v[138:139]
	global_store_dwordx4 v[112:113], v[108:111], off offset:-3072 nt

.LBB0_689:
	s_andn2_b64 vcc, exec, s[42:43]
	v_mad_i64_i32 v[106:107], s[42:43], v106, s61, 0
	s_cbranch_vccnz .LBB0_691
	v_cvt_pk_bf16_f32 v100, v100, v101
	v_cvt_pk_bf16_f32 v101, v102, v103
	v_cvt_pk_bf16_f32 v102, v96, v97
	v_lshl_add_u64 v[96:97], s[24:25], 0, v[106:107]
	v_lshl_add_u64 v[96:97], s[38:39], 1, v[96:97]
	v_lshlrev_b32_e32 v138, 1, v146
	v_lshl_add_u64 v[96:97], v[96:97], 0, v[138:139]
	v_cvt_pk_bf16_f32 v103, v98, v99
	global_store_dwordx4 v[96:97], v[100:103], off nt

.LBB0_697:
	s_andn2_b64 vcc, exec, s[44:45]
	s_cbranch_vccnz .LBB0_699
	v_lshlrev_b32_e32 v138, 1, v146
	v_lshl_add_u64 v[92:93], v[100:101], 0, v[138:139]
	global_store_dwordx4 v[92:93], v[88:91], off offset:256 nt
.LBB0_699:
	s_nop 1
	v_or_b32_e32 v90, 48, v162
	v_ashrrev_i32_e32 v91, 31, v90
	v_mov_b32_e32 v92, v167
	v_lshlrev_b64 v[88:89], 11, v[90:91]
	v_pk_mul_f32 v[86:87], v[86:87], v[92:93] op_sel_hi:[1,0]
	v_pk_mul_f32 v[84:85], v[84:85], v[92:93] op_sel_hi:[1,0]
	v_pk_mul_f32 v[82:83], v[82:83], v[92:93] op_sel_hi:[1,0]
	v_pk_mul_f32 v[80:81], v[80:81], v[92:93] op_sel_hi:[1,0]
	s_and_b64 vcc, exec, s[8:9]
	s_mov_b64 s[42:43], -1
	s_cbranch_vccnz .LBB0_707
	s_andn2_b64 vcc, exec, s[40:41]
	s_cbranch_vccnz .LBB0_704
	s_and_saveexec_b64 s[42:43], s[4:5]
	s_cbranch_execz .LBB0_703
	v_mul_f32_e32 v93, 0xbfb8aa3b, v86
	v_exp_f32_e32 v94, v93
	v_mul_f32_e32 v93, 0xbfb8aa3b, v87
	v_exp_f32_e32 v95, v93
	v_mul_f32_e32 v91, 0xbfb8aa3b, v84
	v_exp_f32_e32 v92, v91
	v_mul_f32_e32 v91, 0xbfb8aa3b, v80
	v_exp_f32_e32 v96, v91
	v_mul_f32_e32 v91, 0xbfb8aa3b, v85
	v_exp_f32_e32 v93, v91
	v_mul_f32_e32 v91, 0xbfb8aa3b, v81
	v_pk_add_f32 v[94:95], v[94:95], 1.0 op_sel_hi:[1,0]
	v_exp_f32_e32 v97, v91
	v_div_scale_f32 v91, s[44:45], v95, v95, 1.0
	v_rcp_f32_e32 v99, v91
	v_pk_add_f32 v[92:93], v[92:93], 1.0 op_sel_hi:[1,0]
	v_mul_f32_e32 v98, 0xbfb8aa3b, v82
	v_exp_f32_e32 v98, v98
	v_fma_f32 v100, -v91, v99, 1.0
	v_fmac_f32_e32 v99, v100, v99
	v_div_scale_f32 v100, vcc, 1.0, v95, 1.0
	v_mul_f32_e32 v101, v100, v99
	v_fma_f32 v102, -v91, v101, v100
	v_fmac_f32_e32 v101, v102, v99
	v_fma_f32 v91, -v91, v101, v100
	v_div_scale_f32 v100, s[44:45], v94, v94, 1.0
	v_rcp_f32_e32 v102, v100
	v_div_fmas_f32 v91, v91, v99, v101
	v_div_fixup_f32 v95, v91, v95, 1.0
	v_pk_add_f32 v[96:97], v[96:97], 1.0 op_sel_hi:[1,0]
	v_fma_f32 v91, -v100, v102, 1.0
	v_fmac_f32_e32 v102, v91, v102
	v_div_scale_f32 v91, vcc, 1.0, v94, 1.0
	v_mul_f32_e32 v99, v91, v102
	v_fma_f32 v101, -v100, v99, v91
	v_fmac_f32_e32 v99, v101, v102
	v_fma_f32 v91, -v100, v99, v91
	v_div_scale_f32 v100, s[44:45], v93, v93, 1.0
	v_rcp_f32_e32 v101, v100
	v_div_fmas_f32 v91, v91, v102, v99
	v_div_fixup_f32 v94, v91, v94, 1.0
	v_fma_f32 v91, -v100, v101, 1.0
	v_fmac_f32_e32 v101, v91, v101
	v_div_scale_f32 v91, vcc, 1.0, v93, 1.0
	v_mul_f32_e32 v99, v91, v101
	v_fma_f32 v102, -v100, v99, v91
	v_fmac_f32_e32 v99, v102, v101
	v_fma_f32 v91, -v100, v99, v91
	v_div_scale_f32 v100, s[44:45], v92, v92, 1.0
	v_rcp_f32_e32 v102, v100
	v_div_fmas_f32 v91, v91, v101, v99
	v_mul_f32_e32 v99, 0xbfb8aa3b, v83
	v_div_fixup_f32 v93, v91, v93, 1.0
	v_fma_f32 v91, -v100, v102, 1.0
	v_exp_f32_e32 v99, v99
	v_fmac_f32_e32 v102, v91, v102
	v_div_scale_f32 v91, vcc, 1.0, v92, 1.0
	v_mul_f32_e32 v101, v91, v102
	v_fma_f32 v103, -v100, v101, v91
	v_fmac_f32_e32 v101, v103, v102
	v_pk_add_f32 v[98:99], v[98:99], 1.0 op_sel_hi:[1,0]
	v_fma_f32 v91, -v100, v101, v91
	v_div_scale_f32 v100, s[44:45], v99, v99, 1.0
	v_rcp_f32_e32 v103, v100
	v_div_fmas_f32 v91, v91, v102, v101
	v_div_fixup_f32 v92, v91, v92, 1.0
	v_fma_f32 v91, -v100, v103, 1.0
	v_fmac_f32_e32 v103, v91, v103
	v_div_scale_f32 v91, vcc, 1.0, v99, 1.0
	v_mul_f32_e32 v101, v91, v103
	v_fma_f32 v102, -v100, v101, v91
	v_fmac_f32_e32 v101, v102, v103
	v_fma_f32 v91, -v100, v101, v91
	v_div_scale_f32 v100, s[44:45], v98, v98, 1.0
	v_rcp_f32_e32 v102, v100
	v_div_fmas_f32 v91, v91, v103, v101
	v_div_fixup_f32 v99, v91, v99, 1.0
	v_fma_f32 v91, -v100, v102, 1.0
	v_fmac_f32_e32 v102, v91, v102
	v_div_scale_f32 v91, vcc, 1.0, v98, 1.0
	v_mul_f32_e32 v101, v91, v102
	v_fma_f32 v103, -v100, v101, v91
	v_fmac_f32_e32 v101, v103, v102
	v_fma_f32 v91, -v100, v101, v91
	v_div_scale_f32 v100, s[44:45], v97, v97, 1.0
	v_rcp_f32_e32 v103, v100
	v_div_fmas_f32 v91, v91, v102, v101
	v_div_fixup_f32 v98, v91, v98, 1.0
	v_fma_f32 v91, -v100, v103, 1.0
	v_fmac_f32_e32 v103, v91, v103
	v_div_scale_f32 v91, vcc, 1.0, v97, 1.0
	v_mul_f32_e32 v101, v91, v103
	v_fma_f32 v102, -v100, v101, v91
	v_fmac_f32_e32 v101, v102, v103
	v_fma_f32 v91, -v100, v101, v91
	v_div_scale_f32 v100, s[44:45], v96, v96, 1.0
	v_rcp_f32_e32 v102, v100
	v_div_fmas_f32 v91, v91, v103, v101
	v_div_fixup_f32 v97, v91, v97, 1.0
	v_fma_f32 v91, -v100, v102, 1.0
	v_fmac_f32_e32 v102, v91, v102
	v_div_scale_f32 v91, vcc, 1.0, v96, 1.0
	v_mul_f32_e32 v101, v91, v102
	v_fma_f32 v103, -v100, v101, v91
	v_fmac_f32_e32 v101, v103, v102
	v_fma_f32 v91, -v100, v101, v91
	v_div_fmas_f32 v91, v91, v102, v101
	v_mad_i64_i32 v[100:101], s[44:45], v90, s53, v[150:151]
	v_div_fixup_f32 v96, v91, v96, 1.0
	global_store_dwordx4 v[100:101], v[92:95], off nt
	global_store_dwordx4 v[100:101], v[96:99], off offset:16 nt

.LBB0_704:
	s_andn2_b64 vcc, exec, s[42:43]
	s_cbranch_vccnz .LBB0_706
	v_pk_mul_f32 v[94:95], v[86:87], s[18:19] op_sel_hi:[1,0]
	v_pk_mul_f32 v[92:93], v[84:85], s[18:19] op_sel_hi:[1,0]
	v_pk_mul_f32 v[96:97], v[82:83], s[18:19] op_sel_hi:[1,0]
	v_pk_mul_f32 v[98:99], v[80:81], s[18:19] op_sel_hi:[1,0]
	v_cvt_pk_bf16_f32 v92, v92, v93
	v_cvt_pk_bf16_f32 v93, v94, v95
	v_lshlrev_b32_e32 v138, 1, v146
	v_cvt_pk_bf16_f32 v94, v98, v99
	v_cvt_pk_bf16_f32 v95, v96, v97
	v_lshl_add_u64 v[96:97], s[10:11], 0, v[88:89]
	v_lshl_add_u64 v[96:97], s[14:15], 1, v[96:97]
	v_lshl_add_u64 v[96:97], v[96:97], 0, v[138:139]
	global_store_dwordx4 v[96:97], v[92:95], off offset:-3072 nt

.LBB0_707:
	s_andn2_b64 vcc, exec, s[42:43]
	v_mad_i64_i32 v[90:91], s[42:43], v90, s61, 0
	s_cbranch_vccnz .LBB0_709
	v_cvt_pk_bf16_f32 v84, v84, v85
	v_cvt_pk_bf16_f32 v85, v86, v87
	v_cvt_pk_bf16_f32 v86, v80, v81
	v_lshl_add_u64 v[80:81], s[24:25], 0, v[90:91]
	v_lshl_add_u64 v[80:81], s[38:39], 1, v[80:81]
	v_lshlrev_b32_e32 v138, 1, v146
	v_lshl_add_u64 v[80:81], v[80:81], 0, v[138:139]
	v_cvt_pk_bf16_f32 v87, v82, v83
	global_store_dwordx4 v[80:81], v[84:87], off nt

.LBB0_715:
	s_andn2_b64 vcc, exec, s[44:45]
	s_cbranch_vccnz .LBB0_717
	v_lshlrev_b32_e32 v138, 1, v146
	v_lshl_add_u64 v[76:77], v[84:85], 0, v[138:139]
	global_store_dwordx4 v[76:77], v[72:75], off offset:256 nt
.LBB0_717:
	s_nop 1
	v_add_u32_e32 v74, 0x80, v162
	v_ashrrev_i32_e32 v75, 31, v74
	v_lshlrev_b64 v[72:73], 11, v[74:75]
	v_pk_mul_f32 v[70:71], v[70:71], v[164:165] op_sel_hi:[1,0]
	v_pk_mul_f32 v[68:69], v[68:69], v[164:165] op_sel_hi:[1,0]
	v_pk_mul_f32 v[66:67], v[66:67], v[164:165] op_sel_hi:[1,0]
	v_pk_mul_f32 v[64:65], v[64:65], v[164:165] op_sel_hi:[1,0]
	s_and_b64 vcc, exec, s[8:9]
	s_mov_b64 s[42:43], -1
	s_cbranch_vccnz .LBB0_725
	s_andn2_b64 vcc, exec, s[40:41]
	s_cbranch_vccnz .LBB0_722
	s_and_saveexec_b64 s[42:43], s[4:5]
	s_cbranch_execz .LBB0_721
	v_mul_f32_e32 v77, 0xbfb8aa3b, v70
	v_exp_f32_e32 v78, v77
	v_mul_f32_e32 v77, 0xbfb8aa3b, v71
	v_exp_f32_e32 v79, v77
	v_mul_f32_e32 v75, 0xbfb8aa3b, v68
	v_exp_f32_e32 v76, v75
	v_mul_f32_e32 v75, 0xbfb8aa3b, v64
	v_exp_f32_e32 v80, v75
	v_mul_f32_e32 v75, 0xbfb8aa3b, v69
	v_exp_f32_e32 v77, v75
	v_mul_f32_e32 v75, 0xbfb8aa3b, v65
	v_pk_add_f32 v[78:79], v[78:79], 1.0 op_sel_hi:[1,0]
	v_exp_f32_e32 v81, v75
	v_div_scale_f32 v75, s[44:45], v79, v79, 1.0
	v_rcp_f32_e32 v83, v75
	v_pk_add_f32 v[76:77], v[76:77], 1.0 op_sel_hi:[1,0]
	v_mul_f32_e32 v82, 0xbfb8aa3b, v66
	v_exp_f32_e32 v82, v82
	v_fma_f32 v84, -v75, v83, 1.0
	v_fmac_f32_e32 v83, v84, v83
	v_div_scale_f32 v84, vcc, 1.0, v79, 1.0
	v_mul_f32_e32 v85, v84, v83
	v_fma_f32 v86, -v75, v85, v84
	v_fmac_f32_e32 v85, v86, v83
	v_fma_f32 v75, -v75, v85, v84
	v_div_scale_f32 v84, s[44:45], v78, v78, 1.0
	v_rcp_f32_e32 v86, v84
	v_div_fmas_f32 v75, v75, v83, v85
	v_div_fixup_f32 v79, v75, v79, 1.0
	v_pk_add_f32 v[80:81], v[80:81], 1.0 op_sel_hi:[1,0]
	v_fma_f32 v75, -v84, v86, 1.0
	v_fmac_f32_e32 v86, v75, v86
	v_div_scale_f32 v75, vcc, 1.0, v78, 1.0
	v_mul_f32_e32 v83, v75, v86
	v_fma_f32 v85, -v84, v83, v75
	v_fmac_f32_e32 v83, v85, v86
	v_fma_f32 v75, -v84, v83, v75
	v_div_scale_f32 v84, s[44:45], v77, v77, 1.0
	v_rcp_f32_e32 v85, v84
	v_div_fmas_f32 v75, v75, v86, v83
	v_div_fixup_f32 v78, v75, v78, 1.0
	v_fma_f32 v75, -v84, v85, 1.0
	v_fmac_f32_e32 v85, v75, v85
	v_div_scale_f32 v75, vcc, 1.0, v77, 1.0
	v_mul_f32_e32 v83, v75, v85
	v_fma_f32 v86, -v84, v83, v75
	v_fmac_f32_e32 v83, v86, v85
	v_fma_f32 v75, -v84, v83, v75
	v_div_scale_f32 v84, s[44:45], v76, v76, 1.0
	v_rcp_f32_e32 v86, v84
	v_div_fmas_f32 v75, v75, v85, v83
	v_mul_f32_e32 v83, 0xbfb8aa3b, v67
	v_div_fixup_f32 v77, v75, v77, 1.0
	v_fma_f32 v75, -v84, v86, 1.0
	v_exp_f32_e32 v83, v83
	v_fmac_f32_e32 v86, v75, v86
	v_div_scale_f32 v75, vcc, 1.0, v76, 1.0
	v_mul_f32_e32 v85, v75, v86
	v_fma_f32 v87, -v84, v85, v75
	v_fmac_f32_e32 v85, v87, v86
	v_pk_add_f32 v[82:83], v[82:83], 1.0 op_sel_hi:[1,0]
	v_fma_f32 v75, -v84, v85, v75
	v_div_scale_f32 v84, s[44:45], v83, v83, 1.0
	v_rcp_f32_e32 v87, v84
	v_div_fmas_f32 v75, v75, v86, v85
	v_div_fixup_f32 v76, v75, v76, 1.0
	v_fma_f32 v75, -v84, v87, 1.0
	v_fmac_f32_e32 v87, v75, v87
	v_div_scale_f32 v75, vcc, 1.0, v83, 1.0
	v_mul_f32_e32 v85, v75, v87
	v_fma_f32 v86, -v84, v85, v75
	v_fmac_f32_e32 v85, v86, v87
	v_fma_f32 v75, -v84, v85, v75
	v_div_scale_f32 v84, s[44:45], v82, v82, 1.0
	v_rcp_f32_e32 v86, v84
	v_div_fmas_f32 v75, v75, v87, v85
	v_div_fixup_f32 v83, v75, v83, 1.0
	v_fma_f32 v75, -v84, v86, 1.0
	v_fmac_f32_e32 v86, v75, v86
	v_div_scale_f32 v75, vcc, 1.0, v82, 1.0
	v_mul_f32_e32 v85, v75, v86
	v_fma_f32 v87, -v84, v85, v75
	v_fmac_f32_e32 v85, v87, v86
	v_fma_f32 v75, -v84, v85, v75
	v_div_scale_f32 v84, s[44:45], v81, v81, 1.0
	v_rcp_f32_e32 v87, v84
	v_div_fmas_f32 v75, v75, v86, v85
	v_div_fixup_f32 v82, v75, v82, 1.0
	v_fma_f32 v75, -v84, v87, 1.0
	v_fmac_f32_e32 v87, v75, v87
	v_div_scale_f32 v75, vcc, 1.0, v81, 1.0
	v_mul_f32_e32 v85, v75, v87
	v_fma_f32 v86, -v84, v85, v75
	v_fmac_f32_e32 v85, v86, v87
	v_fma_f32 v75, -v84, v85, v75
	v_div_scale_f32 v84, s[44:45], v80, v80, 1.0
	v_rcp_f32_e32 v86, v84
	v_div_fmas_f32 v75, v75, v87, v85
	v_div_fixup_f32 v81, v75, v81, 1.0
	v_fma_f32 v75, -v84, v86, 1.0
	v_fmac_f32_e32 v86, v75, v86
	v_div_scale_f32 v75, vcc, 1.0, v80, 1.0
	v_mul_f32_e32 v85, v75, v86
	v_fma_f32 v87, -v84, v85, v75
	v_fmac_f32_e32 v85, v87, v86
	v_fma_f32 v75, -v84, v85, v75
	v_div_fmas_f32 v75, v75, v86, v85
	v_mad_i64_i32 v[84:85], s[44:45], v74, s53, v[150:151]
	v_div_fixup_f32 v80, v75, v80, 1.0
	global_store_dwordx4 v[84:85], v[76:79], off nt
	global_store_dwordx4 v[84:85], v[80:83], off offset:16 nt

.LBB0_722:
	s_andn2_b64 vcc, exec, s[42:43]
	s_cbranch_vccnz .LBB0_724
	v_pk_mul_f32 v[78:79], v[70:71], s[18:19] op_sel_hi:[1,0]
	v_pk_mul_f32 v[76:77], v[68:69], s[18:19] op_sel_hi:[1,0]
	v_pk_mul_f32 v[80:81], v[66:67], s[18:19] op_sel_hi:[1,0]
	v_pk_mul_f32 v[82:83], v[64:65], s[18:19] op_sel_hi:[1,0]
	v_cvt_pk_bf16_f32 v76, v76, v77
	v_cvt_pk_bf16_f32 v77, v78, v79
	v_lshlrev_b32_e32 v138, 1, v146
	v_cvt_pk_bf16_f32 v78, v82, v83
	v_cvt_pk_bf16_f32 v79, v80, v81
	v_lshl_add_u64 v[80:81], s[10:11], 0, v[72:73]
	v_lshl_add_u64 v[80:81], s[14:15], 1, v[80:81]
	v_lshl_add_u64 v[80:81], v[80:81], 0, v[138:139]
	global_store_dwordx4 v[80:81], v[76:79], off offset:-3072 nt

.LBB0_725:
	s_andn2_b64 vcc, exec, s[42:43]
	v_mad_i64_i32 v[74:75], s[42:43], v74, s61, 0
	s_cbranch_vccnz .LBB0_727
	v_cvt_pk_bf16_f32 v68, v68, v69
	v_cvt_pk_bf16_f32 v69, v70, v71
	v_cvt_pk_bf16_f32 v70, v64, v65
	v_lshl_add_u64 v[64:65], s[24:25], 0, v[74:75]
	v_lshl_add_u64 v[64:65], s[38:39], 1, v[64:65]
	v_lshlrev_b32_e32 v138, 1, v146
	v_lshl_add_u64 v[64:65], v[64:65], 0, v[138:139]
	v_cvt_pk_bf16_f32 v71, v66, v67
	global_store_dwordx4 v[64:65], v[68:71], off nt

.LBB0_733:
	s_andn2_b64 vcc, exec, s[44:45]
	s_cbranch_vccnz .LBB0_735
	v_lshlrev_b32_e32 v138, 1, v146
	v_lshl_add_u64 v[60:61], v[68:69], 0, v[138:139]
	global_store_dwordx4 v[60:61], v[56:59], off offset:256 nt
.LBB0_735:
	s_nop 1
	v_add_u32_e32 v58, 0x90, v162
	v_ashrrev_i32_e32 v59, 31, v58
	v_mov_b32_e32 v60, v165
	v_lshlrev_b64 v[56:57], 11, v[58:59]
	v_pk_mul_f32 v[54:55], v[54:55], v[60:61] op_sel_hi:[1,0]
	v_pk_mul_f32 v[52:53], v[52:53], v[60:61] op_sel_hi:[1,0]
	v_pk_mul_f32 v[50:51], v[50:51], v[60:61] op_sel_hi:[1,0]
	v_pk_mul_f32 v[48:49], v[48:49], v[60:61] op_sel_hi:[1,0]
	s_and_b64 vcc, exec, s[8:9]
	s_mov_b64 s[42:43], -1
	s_cbranch_vccnz .LBB0_743
	s_andn2_b64 vcc, exec, s[40:41]
	s_cbranch_vccnz .LBB0_740
	s_and_saveexec_b64 s[42:43], s[4:5]
	s_cbranch_execz .LBB0_739
	v_mul_f32_e32 v61, 0xbfb8aa3b, v54
	v_exp_f32_e32 v62, v61
	v_mul_f32_e32 v61, 0xbfb8aa3b, v55
	v_exp_f32_e32 v63, v61
	v_mul_f32_e32 v59, 0xbfb8aa3b, v52
	v_exp_f32_e32 v60, v59
	v_mul_f32_e32 v59, 0xbfb8aa3b, v48
	v_exp_f32_e32 v64, v59
	v_mul_f32_e32 v59, 0xbfb8aa3b, v53
	v_exp_f32_e32 v61, v59
	v_mul_f32_e32 v59, 0xbfb8aa3b, v49
	v_pk_add_f32 v[62:63], v[62:63], 1.0 op_sel_hi:[1,0]
	v_exp_f32_e32 v65, v59
	v_div_scale_f32 v59, s[44:45], v63, v63, 1.0
	v_rcp_f32_e32 v67, v59
	v_pk_add_f32 v[60:61], v[60:61], 1.0 op_sel_hi:[1,0]
	v_mul_f32_e32 v66, 0xbfb8aa3b, v50
	v_exp_f32_e32 v66, v66
	v_fma_f32 v68, -v59, v67, 1.0
	v_fmac_f32_e32 v67, v68, v67
	v_div_scale_f32 v68, vcc, 1.0, v63, 1.0
	v_mul_f32_e32 v69, v68, v67
	v_fma_f32 v70, -v59, v69, v68
	v_fmac_f32_e32 v69, v70, v67
	v_fma_f32 v59, -v59, v69, v68
	v_div_scale_f32 v68, s[44:45], v62, v62, 1.0
	v_rcp_f32_e32 v70, v68
	v_div_fmas_f32 v59, v59, v67, v69
	v_div_fixup_f32 v63, v59, v63, 1.0
	v_pk_add_f32 v[64:65], v[64:65], 1.0 op_sel_hi:[1,0]
	v_fma_f32 v59, -v68, v70, 1.0
	v_fmac_f32_e32 v70, v59, v70
	v_div_scale_f32 v59, vcc, 1.0, v62, 1.0
	v_mul_f32_e32 v67, v59, v70
	v_fma_f32 v69, -v68, v67, v59
	v_fmac_f32_e32 v67, v69, v70
	v_fma_f32 v59, -v68, v67, v59
	v_div_scale_f32 v68, s[44:45], v61, v61, 1.0
	v_rcp_f32_e32 v69, v68
	v_div_fmas_f32 v59, v59, v70, v67
	v_div_fixup_f32 v62, v59, v62, 1.0
	v_fma_f32 v59, -v68, v69, 1.0
	v_fmac_f32_e32 v69, v59, v69
	v_div_scale_f32 v59, vcc, 1.0, v61, 1.0
	v_mul_f32_e32 v67, v59, v69
	v_fma_f32 v70, -v68, v67, v59
	v_fmac_f32_e32 v67, v70, v69
	v_fma_f32 v59, -v68, v67, v59
	v_div_scale_f32 v68, s[44:45], v60, v60, 1.0
	v_rcp_f32_e32 v70, v68
	v_div_fmas_f32 v59, v59, v69, v67
	v_mul_f32_e32 v67, 0xbfb8aa3b, v51
	v_div_fixup_f32 v61, v59, v61, 1.0
	v_fma_f32 v59, -v68, v70, 1.0
	v_exp_f32_e32 v67, v67
	v_fmac_f32_e32 v70, v59, v70
	v_div_scale_f32 v59, vcc, 1.0, v60, 1.0
	v_mul_f32_e32 v69, v59, v70
	v_fma_f32 v71, -v68, v69, v59
	v_fmac_f32_e32 v69, v71, v70
	v_pk_add_f32 v[66:67], v[66:67], 1.0 op_sel_hi:[1,0]
	v_fma_f32 v59, -v68, v69, v59
	v_div_scale_f32 v68, s[44:45], v67, v67, 1.0
	v_rcp_f32_e32 v71, v68
	v_div_fmas_f32 v59, v59, v70, v69
	v_div_fixup_f32 v60, v59, v60, 1.0
	v_fma_f32 v59, -v68, v71, 1.0
	v_fmac_f32_e32 v71, v59, v71
	v_div_scale_f32 v59, vcc, 1.0, v67, 1.0
	v_mul_f32_e32 v69, v59, v71
	v_fma_f32 v70, -v68, v69, v59
	v_fmac_f32_e32 v69, v70, v71
	v_fma_f32 v59, -v68, v69, v59
	v_div_scale_f32 v68, s[44:45], v66, v66, 1.0
	v_rcp_f32_e32 v70, v68
	v_div_fmas_f32 v59, v59, v71, v69
	v_div_fixup_f32 v67, v59, v67, 1.0
	v_fma_f32 v59, -v68, v70, 1.0
	v_fmac_f32_e32 v70, v59, v70
	v_div_scale_f32 v59, vcc, 1.0, v66, 1.0
	v_mul_f32_e32 v69, v59, v70
	v_fma_f32 v71, -v68, v69, v59
	v_fmac_f32_e32 v69, v71, v70
	v_fma_f32 v59, -v68, v69, v59
	v_div_scale_f32 v68, s[44:45], v65, v65, 1.0
	v_rcp_f32_e32 v71, v68
	v_div_fmas_f32 v59, v59, v70, v69
	v_div_fixup_f32 v66, v59, v66, 1.0
	v_fma_f32 v59, -v68, v71, 1.0
	v_fmac_f32_e32 v71, v59, v71
	v_div_scale_f32 v59, vcc, 1.0, v65, 1.0
	v_mul_f32_e32 v69, v59, v71
	v_fma_f32 v70, -v68, v69, v59
	v_fmac_f32_e32 v69, v70, v71
	v_fma_f32 v59, -v68, v69, v59
	v_div_scale_f32 v68, s[44:45], v64, v64, 1.0
	v_rcp_f32_e32 v70, v68
	v_div_fmas_f32 v59, v59, v71, v69
	v_div_fixup_f32 v65, v59, v65, 1.0
	v_fma_f32 v59, -v68, v70, 1.0
	v_fmac_f32_e32 v70, v59, v70
	v_div_scale_f32 v59, vcc, 1.0, v64, 1.0
	v_mul_f32_e32 v69, v59, v70
	v_fma_f32 v71, -v68, v69, v59
	v_fmac_f32_e32 v69, v71, v70
	v_fma_f32 v59, -v68, v69, v59
	v_div_fmas_f32 v59, v59, v70, v69
	v_mad_i64_i32 v[68:69], s[44:45], v58, s53, v[150:151]
	v_div_fixup_f32 v64, v59, v64, 1.0
	global_store_dwordx4 v[68:69], v[60:63], off nt
	global_store_dwordx4 v[68:69], v[64:67], off offset:16 nt

.LBB0_740:
	s_andn2_b64 vcc, exec, s[42:43]
	s_cbranch_vccnz .LBB0_742
	v_pk_mul_f32 v[62:63], v[54:55], s[18:19] op_sel_hi:[1,0]
	v_pk_mul_f32 v[60:61], v[52:53], s[18:19] op_sel_hi:[1,0]
	v_pk_mul_f32 v[64:65], v[50:51], s[18:19] op_sel_hi:[1,0]
	v_pk_mul_f32 v[66:67], v[48:49], s[18:19] op_sel_hi:[1,0]
	v_cvt_pk_bf16_f32 v60, v60, v61
	v_cvt_pk_bf16_f32 v61, v62, v63
	v_lshlrev_b32_e32 v138, 1, v146
	v_cvt_pk_bf16_f32 v62, v66, v67
	v_cvt_pk_bf16_f32 v63, v64, v65
	v_lshl_add_u64 v[64:65], s[10:11], 0, v[56:57]
	v_lshl_add_u64 v[64:65], s[14:15], 1, v[64:65]
	v_lshl_add_u64 v[64:65], v[64:65], 0, v[138:139]
	global_store_dwordx4 v[64:65], v[60:63], off offset:-3072 nt

.LBB0_743:
	s_andn2_b64 vcc, exec, s[42:43]
	v_mad_i64_i32 v[58:59], s[42:43], v58, s61, 0
	s_cbranch_vccnz .LBB0_745
	v_cvt_pk_bf16_f32 v52, v52, v53
	v_cvt_pk_bf16_f32 v53, v54, v55
	v_cvt_pk_bf16_f32 v54, v48, v49
	v_lshl_add_u64 v[48:49], s[24:25], 0, v[58:59]
	v_lshl_add_u64 v[48:49], s[38:39], 1, v[48:49]
	v_lshlrev_b32_e32 v138, 1, v146
	v_lshl_add_u64 v[48:49], v[48:49], 0, v[138:139]
	v_cvt_pk_bf16_f32 v55, v50, v51
	global_store_dwordx4 v[48:49], v[52:55], off nt

.LBB0_751:
	s_andn2_b64 vcc, exec, s[44:45]
	s_cbranch_vccnz .LBB0_753
	v_lshlrev_b32_e32 v138, 1, v146
	v_lshl_add_u64 v[44:45], v[52:53], 0, v[138:139]
	global_store_dwordx4 v[44:45], v[40:43], off offset:256 nt
.LBB0_753:
	s_nop 1
	v_add_u32_e32 v42, 0xa0, v162
	v_ashrrev_i32_e32 v43, 31, v42
	v_lshlrev_b64 v[40:41], 11, v[42:43]
	v_pk_mul_f32 v[38:39], v[38:39], v[160:161] op_sel_hi:[1,0]
	v_pk_mul_f32 v[36:37], v[36:37], v[160:161] op_sel_hi:[1,0]
	v_pk_mul_f32 v[34:35], v[34:35], v[160:161] op_sel_hi:[1,0]
	v_pk_mul_f32 v[32:33], v[32:33], v[160:161] op_sel_hi:[1,0]
	s_and_b64 vcc, exec, s[8:9]
	s_mov_b64 s[42:43], -1
	s_cbranch_vccnz .LBB0_761
	s_andn2_b64 vcc, exec, s[40:41]
	s_cbranch_vccnz .LBB0_758
	s_and_saveexec_b64 s[42:43], s[4:5]
	s_cbranch_execz .LBB0_757
	v_mul_f32_e32 v45, 0xbfb8aa3b, v38
	v_exp_f32_e32 v46, v45
	v_mul_f32_e32 v45, 0xbfb8aa3b, v39
	v_exp_f32_e32 v47, v45
	v_mul_f32_e32 v43, 0xbfb8aa3b, v36
	v_exp_f32_e32 v44, v43
	v_mul_f32_e32 v43, 0xbfb8aa3b, v32
	v_exp_f32_e32 v48, v43
	v_mul_f32_e32 v43, 0xbfb8aa3b, v37
	v_exp_f32_e32 v45, v43
	v_mul_f32_e32 v43, 0xbfb8aa3b, v33
	v_pk_add_f32 v[46:47], v[46:47], 1.0 op_sel_hi:[1,0]
	v_exp_f32_e32 v49, v43
	v_div_scale_f32 v43, s[44:45], v47, v47, 1.0
	v_rcp_f32_e32 v51, v43
	v_pk_add_f32 v[44:45], v[44:45], 1.0 op_sel_hi:[1,0]
	v_mul_f32_e32 v50, 0xbfb8aa3b, v34
	v_exp_f32_e32 v50, v50
	v_fma_f32 v52, -v43, v51, 1.0
	v_fmac_f32_e32 v51, v52, v51
	v_div_scale_f32 v52, vcc, 1.0, v47, 1.0
	v_mul_f32_e32 v53, v52, v51
	v_fma_f32 v54, -v43, v53, v52
	v_fmac_f32_e32 v53, v54, v51
	v_fma_f32 v43, -v43, v53, v52
	v_div_scale_f32 v52, s[44:45], v46, v46, 1.0
	v_rcp_f32_e32 v54, v52
	v_div_fmas_f32 v43, v43, v51, v53
	v_div_fixup_f32 v47, v43, v47, 1.0
	v_pk_add_f32 v[48:49], v[48:49], 1.0 op_sel_hi:[1,0]
	v_fma_f32 v43, -v52, v54, 1.0
	v_fmac_f32_e32 v54, v43, v54
	v_div_scale_f32 v43, vcc, 1.0, v46, 1.0
	v_mul_f32_e32 v51, v43, v54
	v_fma_f32 v53, -v52, v51, v43
	v_fmac_f32_e32 v51, v53, v54
	v_fma_f32 v43, -v52, v51, v43
	v_div_scale_f32 v52, s[44:45], v45, v45, 1.0
	v_rcp_f32_e32 v53, v52
	v_div_fmas_f32 v43, v43, v54, v51
	v_div_fixup_f32 v46, v43, v46, 1.0
	v_fma_f32 v43, -v52, v53, 1.0
	v_fmac_f32_e32 v53, v43, v53
	v_div_scale_f32 v43, vcc, 1.0, v45, 1.0
	v_mul_f32_e32 v51, v43, v53
	v_fma_f32 v54, -v52, v51, v43
	v_fmac_f32_e32 v51, v54, v53
	v_fma_f32 v43, -v52, v51, v43
	v_div_scale_f32 v52, s[44:45], v44, v44, 1.0
	v_rcp_f32_e32 v54, v52
	v_div_fmas_f32 v43, v43, v53, v51
	v_mul_f32_e32 v51, 0xbfb8aa3b, v35
	v_div_fixup_f32 v45, v43, v45, 1.0
	v_fma_f32 v43, -v52, v54, 1.0
	v_exp_f32_e32 v51, v51
	v_fmac_f32_e32 v54, v43, v54
	v_div_scale_f32 v43, vcc, 1.0, v44, 1.0
	v_mul_f32_e32 v53, v43, v54
	v_fma_f32 v55, -v52, v53, v43
	v_fmac_f32_e32 v53, v55, v54
	v_pk_add_f32 v[50:51], v[50:51], 1.0 op_sel_hi:[1,0]
	v_fma_f32 v43, -v52, v53, v43
	v_div_scale_f32 v52, s[44:45], v51, v51, 1.0
	v_rcp_f32_e32 v55, v52
	v_div_fmas_f32 v43, v43, v54, v53
	v_div_fixup_f32 v44, v43, v44, 1.0
	v_fma_f32 v43, -v52, v55, 1.0
	v_fmac_f32_e32 v55, v43, v55
	v_div_scale_f32 v43, vcc, 1.0, v51, 1.0
	v_mul_f32_e32 v53, v43, v55
	v_fma_f32 v54, -v52, v53, v43
	v_fmac_f32_e32 v53, v54, v55
	v_fma_f32 v43, -v52, v53, v43
	v_div_scale_f32 v52, s[44:45], v50, v50, 1.0
	v_rcp_f32_e32 v54, v52
	v_div_fmas_f32 v43, v43, v55, v53
	v_div_fixup_f32 v51, v43, v51, 1.0
	v_fma_f32 v43, -v52, v54, 1.0
	v_fmac_f32_e32 v54, v43, v54
	v_div_scale_f32 v43, vcc, 1.0, v50, 1.0
	v_mul_f32_e32 v53, v43, v54
	v_fma_f32 v55, -v52, v53, v43
	v_fmac_f32_e32 v53, v55, v54
	v_fma_f32 v43, -v52, v53, v43
	v_div_scale_f32 v52, s[44:45], v49, v49, 1.0
	v_rcp_f32_e32 v55, v52
	v_div_fmas_f32 v43, v43, v54, v53
	v_div_fixup_f32 v50, v43, v50, 1.0
	v_fma_f32 v43, -v52, v55, 1.0
	v_fmac_f32_e32 v55, v43, v55
	v_div_scale_f32 v43, vcc, 1.0, v49, 1.0
	v_mul_f32_e32 v53, v43, v55
	v_fma_f32 v54, -v52, v53, v43
	v_fmac_f32_e32 v53, v54, v55
	v_fma_f32 v43, -v52, v53, v43
	v_div_scale_f32 v52, s[44:45], v48, v48, 1.0
	v_rcp_f32_e32 v54, v52
	v_div_fmas_f32 v43, v43, v55, v53
	v_div_fixup_f32 v49, v43, v49, 1.0
	v_fma_f32 v43, -v52, v54, 1.0
	v_fmac_f32_e32 v54, v43, v54
	v_div_scale_f32 v43, vcc, 1.0, v48, 1.0
	v_mul_f32_e32 v53, v43, v54
	v_fma_f32 v55, -v52, v53, v43
	v_fmac_f32_e32 v53, v55, v54
	v_fma_f32 v43, -v52, v53, v43
	v_div_fmas_f32 v43, v43, v54, v53
	v_mad_i64_i32 v[52:53], s[44:45], v42, s53, v[150:151]
	v_div_fixup_f32 v48, v43, v48, 1.0
	global_store_dwordx4 v[52:53], v[44:47], off nt
	global_store_dwordx4 v[52:53], v[48:51], off offset:16 nt

.LBB0_758:
	s_andn2_b64 vcc, exec, s[42:43]
	s_cbranch_vccnz .LBB0_760
	v_pk_mul_f32 v[46:47], v[38:39], s[18:19] op_sel_hi:[1,0]
	v_pk_mul_f32 v[44:45], v[36:37], s[18:19] op_sel_hi:[1,0]
	v_pk_mul_f32 v[48:49], v[34:35], s[18:19] op_sel_hi:[1,0]
	v_pk_mul_f32 v[50:51], v[32:33], s[18:19] op_sel_hi:[1,0]
	v_cvt_pk_bf16_f32 v44, v44, v45
	v_cvt_pk_bf16_f32 v45, v46, v47
	v_lshlrev_b32_e32 v138, 1, v146
	v_cvt_pk_bf16_f32 v46, v50, v51
	v_cvt_pk_bf16_f32 v47, v48, v49
	v_lshl_add_u64 v[48:49], s[10:11], 0, v[40:41]
	v_lshl_add_u64 v[48:49], s[14:15], 1, v[48:49]
	v_lshl_add_u64 v[48:49], v[48:49], 0, v[138:139]
	global_store_dwordx4 v[48:49], v[44:47], off offset:-3072 nt

.LBB0_761:
	s_andn2_b64 vcc, exec, s[42:43]
	v_mad_i64_i32 v[42:43], s[42:43], v42, s61, 0
	s_cbranch_vccnz .LBB0_763
	v_cvt_pk_bf16_f32 v36, v36, v37
	v_cvt_pk_bf16_f32 v37, v38, v39
	v_cvt_pk_bf16_f32 v38, v32, v33
	v_lshl_add_u64 v[32:33], s[24:25], 0, v[42:43]
	v_lshl_add_u64 v[32:33], s[38:39], 1, v[32:33]
	v_lshlrev_b32_e32 v138, 1, v146
	v_lshl_add_u64 v[32:33], v[32:33], 0, v[138:139]
	v_cvt_pk_bf16_f32 v39, v34, v35
	global_store_dwordx4 v[32:33], v[36:39], off nt

.LBB0_769:
	s_andn2_b64 vcc, exec, s[44:45]
	s_cbranch_vccnz .LBB0_771
	v_lshlrev_b32_e32 v138, 1, v146
	v_lshl_add_u64 v[20:21], v[36:37], 0, v[138:139]
	global_store_dwordx4 v[20:21], v[16:19], off offset:256 nt
.LBB0_771:
	s_nop 1
	v_add_u32_e32 v18, 0xb0, v162
	v_ashrrev_i32_e32 v19, 31, v18
	v_mov_b32_e32 v20, v161
	v_lshlrev_b64 v[16:17], 11, v[18:19]
	v_pk_mul_f32 v[14:15], v[14:15], v[20:21] op_sel_hi:[1,0]
	v_pk_mul_f32 v[12:13], v[12:13], v[20:21] op_sel_hi:[1,0]
	v_pk_mul_f32 v[10:11], v[10:11], v[20:21] op_sel_hi:[1,0]
	v_pk_mul_f32 v[8:9], v[8:9], v[20:21] op_sel_hi:[1,0]
	s_and_b64 vcc, exec, s[8:9]
	s_mov_b64 s[42:43], -1
	s_cbranch_vccnz .LBB0_779
	s_andn2_b64 vcc, exec, s[40:41]
	s_mov_b64 s[40:41], -1
	s_cbranch_vccnz .LBB0_776
	s_and_saveexec_b64 s[40:41], s[4:5]
	s_cbranch_execz .LBB0_775
	v_mul_f32_e32 v21, 0xbfb8aa3b, v14
	v_exp_f32_e32 v22, v21
	v_mul_f32_e32 v21, 0xbfb8aa3b, v15
	v_exp_f32_e32 v23, v21
	v_mul_f32_e32 v19, 0xbfb8aa3b, v12
	v_exp_f32_e32 v20, v19
	v_mul_f32_e32 v19, 0xbfb8aa3b, v8
	v_exp_f32_e32 v32, v19
	v_mul_f32_e32 v19, 0xbfb8aa3b, v13
	v_exp_f32_e32 v21, v19
	v_mul_f32_e32 v19, 0xbfb8aa3b, v9
	v_pk_add_f32 v[22:23], v[22:23], 1.0 op_sel_hi:[1,0]
	v_exp_f32_e32 v33, v19
	v_div_scale_f32 v19, s[42:43], v23, v23, 1.0
	v_rcp_f32_e32 v35, v19
	v_pk_add_f32 v[20:21], v[20:21], 1.0 op_sel_hi:[1,0]
	v_mul_f32_e32 v34, 0xbfb8aa3b, v10
	v_exp_f32_e32 v34, v34
	v_fma_f32 v36, -v19, v35, 1.0
	v_fmac_f32_e32 v35, v36, v35
	v_div_scale_f32 v36, vcc, 1.0, v23, 1.0
	v_mul_f32_e32 v37, v36, v35
	v_fma_f32 v38, -v19, v37, v36
	v_fmac_f32_e32 v37, v38, v35
	v_fma_f32 v19, -v19, v37, v36
	v_div_scale_f32 v36, s[42:43], v22, v22, 1.0
	v_rcp_f32_e32 v38, v36
	v_div_fmas_f32 v19, v19, v35, v37
	v_div_fixup_f32 v23, v19, v23, 1.0
	v_pk_add_f32 v[32:33], v[32:33], 1.0 op_sel_hi:[1,0]
	v_fma_f32 v19, -v36, v38, 1.0
	v_fmac_f32_e32 v38, v19, v38
	v_div_scale_f32 v19, vcc, 1.0, v22, 1.0
	v_mul_f32_e32 v35, v19, v38
	v_fma_f32 v37, -v36, v35, v19
	v_fmac_f32_e32 v35, v37, v38
	v_fma_f32 v19, -v36, v35, v19
	v_div_scale_f32 v36, s[42:43], v21, v21, 1.0
	v_rcp_f32_e32 v37, v36
	v_div_fmas_f32 v19, v19, v38, v35
	v_div_fixup_f32 v22, v19, v22, 1.0
	v_fma_f32 v19, -v36, v37, 1.0
	v_fmac_f32_e32 v37, v19, v37
	v_div_scale_f32 v19, vcc, 1.0, v21, 1.0
	v_mul_f32_e32 v35, v19, v37
	v_fma_f32 v38, -v36, v35, v19
	v_fmac_f32_e32 v35, v38, v37
	v_fma_f32 v19, -v36, v35, v19
	v_div_scale_f32 v36, s[42:43], v20, v20, 1.0
	v_rcp_f32_e32 v38, v36
	v_div_fmas_f32 v19, v19, v37, v35
	v_mul_f32_e32 v35, 0xbfb8aa3b, v11
	v_div_fixup_f32 v21, v19, v21, 1.0
	v_fma_f32 v19, -v36, v38, 1.0
	v_exp_f32_e32 v35, v35
	v_fmac_f32_e32 v38, v19, v38
	v_div_scale_f32 v19, vcc, 1.0, v20, 1.0
	v_mul_f32_e32 v37, v19, v38
	v_fma_f32 v39, -v36, v37, v19
	v_fmac_f32_e32 v37, v39, v38
	v_pk_add_f32 v[34:35], v[34:35], 1.0 op_sel_hi:[1,0]
	v_fma_f32 v19, -v36, v37, v19
	v_div_scale_f32 v36, s[42:43], v35, v35, 1.0
	v_rcp_f32_e32 v39, v36
	v_div_fmas_f32 v19, v19, v38, v37
	v_div_fixup_f32 v20, v19, v20, 1.0
	v_fma_f32 v19, -v36, v39, 1.0
	v_fmac_f32_e32 v39, v19, v39
	v_div_scale_f32 v19, vcc, 1.0, v35, 1.0
	v_mul_f32_e32 v37, v19, v39
	v_fma_f32 v38, -v36, v37, v19
	v_fmac_f32_e32 v37, v38, v39
	v_fma_f32 v19, -v36, v37, v19
	v_div_scale_f32 v36, s[42:43], v34, v34, 1.0
	v_rcp_f32_e32 v38, v36
	v_div_fmas_f32 v19, v19, v39, v37
	v_div_fixup_f32 v35, v19, v35, 1.0
	v_fma_f32 v19, -v36, v38, 1.0
	v_fmac_f32_e32 v38, v19, v38
	v_div_scale_f32 v19, vcc, 1.0, v34, 1.0
	v_mul_f32_e32 v37, v19, v38
	v_fma_f32 v39, -v36, v37, v19
	v_fmac_f32_e32 v37, v39, v38
	v_fma_f32 v19, -v36, v37, v19
	v_div_scale_f32 v36, s[42:43], v33, v33, 1.0
	v_rcp_f32_e32 v39, v36
	v_div_fmas_f32 v19, v19, v38, v37
	v_div_fixup_f32 v34, v19, v34, 1.0
	v_fma_f32 v19, -v36, v39, 1.0
	v_fmac_f32_e32 v39, v19, v39
	v_div_scale_f32 v19, vcc, 1.0, v33, 1.0
	v_mul_f32_e32 v37, v19, v39
	v_fma_f32 v38, -v36, v37, v19
	v_fmac_f32_e32 v37, v38, v39
	v_fma_f32 v19, -v36, v37, v19
	v_div_scale_f32 v36, s[42:43], v32, v32, 1.0
	v_rcp_f32_e32 v38, v36
	v_div_fmas_f32 v19, v19, v39, v37
	v_div_fixup_f32 v33, v19, v33, 1.0
	v_fma_f32 v19, -v36, v38, 1.0
	v_fmac_f32_e32 v38, v19, v38
	v_div_scale_f32 v19, vcc, 1.0, v32, 1.0
	v_mul_f32_e32 v37, v19, v38
	v_fma_f32 v39, -v36, v37, v19
	v_fmac_f32_e32 v37, v39, v38
	v_fma_f32 v19, -v36, v37, v19
	v_div_fmas_f32 v19, v19, v38, v37
	v_mad_i64_i32 v[36:37], s[42:43], v18, s53, v[150:151]
	v_div_fixup_f32 v32, v19, v32, 1.0
	global_store_dwordx4 v[36:37], v[20:23], off nt
	global_store_dwordx4 v[36:37], v[32:35], off offset:16 nt

.LBB0_776:
	s_andn2_b64 vcc, exec, s[40:41]
	s_cbranch_vccnz .LBB0_778
	v_pk_mul_f32 v[22:23], v[14:15], s[18:19] op_sel_hi:[1,0]
	v_pk_mul_f32 v[20:21], v[12:13], s[18:19] op_sel_hi:[1,0]
	v_pk_mul_f32 v[32:33], v[10:11], s[18:19] op_sel_hi:[1,0]
	v_pk_mul_f32 v[34:35], v[8:9], s[18:19] op_sel_hi:[1,0]
	v_cvt_pk_bf16_f32 v20, v20, v21
	v_cvt_pk_bf16_f32 v21, v22, v23
	v_lshlrev_b32_e32 v138, 1, v146
	v_cvt_pk_bf16_f32 v22, v34, v35
	v_cvt_pk_bf16_f32 v23, v32, v33
	v_lshl_add_u64 v[32:33], s[10:11], 0, v[16:17]
	v_lshl_add_u64 v[32:33], s[14:15], 1, v[32:33]
	v_lshl_add_u64 v[32:33], v[32:33], 0, v[138:139]
	global_store_dwordx4 v[32:33], v[20:23], off offset:-3072 nt

.LBB0_779:
	s_andn2_b64 vcc, exec, s[42:43]
	v_mad_i64_i32 v[18:19], s[40:41], v18, s61, 0
	s_cbranch_vccnz .LBB0_781
	v_cvt_pk_bf16_f32 v12, v12, v13
	v_cvt_pk_bf16_f32 v13, v14, v15
	v_cvt_pk_bf16_f32 v14, v8, v9
	v_lshl_add_u64 v[8:9], s[24:25], 0, v[18:19]
	v_lshl_add_u64 v[8:9], s[38:39], 1, v[8:9]
	v_lshlrev_b32_e32 v138, 1, v146
	v_lshl_add_u64 v[8:9], v[8:9], 0, v[138:139]
	v_cvt_pk_bf16_f32 v15, v10, v11
	global_store_dwordx4 v[8:9], v[12:15], off nt

.LBB0_789:
	v_lshlrev_b32_e32 v138, 1, v146
	v_lshl_add_u64 v[4:5], v[12:13], 0, v[138:139]
	global_store_dwordx4 v[4:5], v[0:3], off offset:256 nt
	s_and_b64 vcc, exec, s[6:7]
	s_mov_b64 s[6:7], -1
	s_cbranch_vccnz .LBB0_638
